# LDS-free cross-half row max in A3 online softmax: ds_bpermute replaced by v_permlane32_swap (on top of v21)
# speedup vs baseline: 1.0056x; 1.0056x over previous
; #define LAS __attribute__((address_space(3)))
; #define MFMA32(a, b, c) __builtin_amdgcn_mfma_f32_32x32x16_bf16((a), (b), (c), 0, 0, 0)
;     ...
;         const int key0 = kt * KT + sub * 32 * NKB;
;         if ((MODE == 0 || key0 <= q0 + 31) && PV != 2) {
;             unsigned long long mw[NKB / 2];
;             if (MODE == 0) {
; #pragma unroll
;                 for (int w = 0; w < NKB / 2; ++w) mw[w] = MASK64[(rowbase + q0 + r) * 32 + (key0 >> 6) + w];
;             }
;             f32x16 sv[NKB];
; #pragma unroll
;             for (int kb2 = 0; kb2 < NKB; ++kb2)
; #pragma unroll
;                 for (int i = 0; i < 16; ++i) sv[kb2][i] = nm_run;
;             const LAS unsigned char* kb_ = lds + st * STAGE + koff + sub * 32 * NKB * KP;
; #pragma unroll
;             for (int kh = 0; kh < 2; ++kh) {
;                 bf16x8 kfr[2][NKB];
; #pragma unroll
;                 for (int k2 = 0; k2 < 2; ++k2)
; #pragma unroll
;                     for (int kb2 = 0; kb2 < NKB; ++kb2) kfr[k2][kb2] = *(const LAS bf16x8*)(kb_ + (32 * kb2 + r) * KP + (2 * kh + k2) * 32 + h * 16);
;                 if (NKB == 2) asm volatile("" : "+v"(kfr[0][0]), "+v"(kfr[0][1]), "+v"(kfr[1][0]), "+v"(kfr[1][1]));
;                 else asm volatile("" : "+v"(kfr[0][0]), "+v"(kfr[0][1]), "+v"(kfr[0][NKB - 2]), "+v"(kfr[0][NKB - 1]), "+v"(kfr[1][0]), "+v"(kfr[1][1]), "+v"(kfr[1][NKB - 2]), "+v"(kfr[1][NKB - 1]));
; #pragma unroll
;                 for (int k2 = 0; k2 < 2; ++k2)
; #pragma unroll
;                     for (int kb2 = 0; kb2 < NKB; ++kb2) sv[kb2] = MFMA32(kfr[k2][kb2], qf[2 * kh + k2], sv[kb2]);
;             }
;             if (MODE == 0) {
; #pragma unroll
;                 for (int kb2 = 0; kb2 < NKB; ++kb2) {
;                     const unsigned wsel = ((kb2 & 1) ? (unsigned)(mw[kb2 >> 1] >> 32) : (unsigned)mw[kb2 >> 1]) >> (4 * h);
; #pragma unroll
;                     for (int i = 0; i < 16; ++i) { const int cb = (i & 3) + 8 * (i >> 2); if (!((wsel >> cb) & 1u)) sv[kb2][i] = -1e30f; }
.LBB0_522:
	v_lshl_add_u64 v[34:35], s[0:1], 0, v[166:167]
	v_add_co_u32_e32 v34, vcc, 0x1d600000, v34
	s_and_b32 s7, s6, 1
	s_nop 0
	v_addc_co_u32_e32 v35, vcc, 0, v35, vcc
	global_load_dwordx4 v[132:135], v[34:35], off
	s_mul_i32 s9, s7, 0x8a00
	s_add_i32 s9, s9, 0
	v_add3_u32 v185, s9, v180, v182
	ds_read_b128 v[186:189], v185 offset:13856
	ds_read_b128 v[190:193], v185 offset:9248
	ds_read_b128 v[200:203], v185 offset:4640
	ds_read_b128 v[204:207], v185 offset:13824
	ds_read_b128 v[208:211], v185 offset:9216
	ds_read_b128 v[48:51], v185 offset:4608
	ds_read_b128 v[52:55], v185
	ds_read_b128 v[212:215], v185 offset:32
	v_mov_b32_e32 v33, v32
	v_mov_b32_e32 v34, v32
	v_mov_b32_e32 v35, v32
	v_mov_b32_e32 v36, v32
	v_mov_b32_e32 v37, v32
	v_mov_b32_e32 v38, v32
	v_mov_b32_e32 v39, v32
	v_mov_b32_e32 v40, v32
	v_mov_b32_e32 v41, v32
	v_mov_b32_e32 v42, v32
	v_mov_b32_e32 v43, v32
	v_mov_b32_e32 v44, v32
	v_mov_b32_e32 v45, v32
	v_mov_b32_e32 v46, v32
	v_mov_b32_e32 v47, v32
	s_waitcnt lgkmcnt(0)
	s_nop 0
	v_mfma_f32_32x32x16_bf16 v[82:97], v[52:55], v[100:103], v[32:47]
	v_mfma_f32_32x32x16_bf16 v[66:81], v[48:51], v[100:103], v[32:47]
	v_mfma_f32_32x32x16_bf16 v[50:65], v[208:211], v[100:103], v[32:47]
	v_mov_b64_e32 v[48:49], v[46:47]
	s_nop 5
	v_mov_b64_e32 v[46:47], v[44:45]
	v_mov_b64_e32 v[44:45], v[42:43]
	v_mov_b64_e32 v[42:43], v[40:41]
	v_mov_b64_e32 v[40:41], v[38:39]
	v_mov_b64_e32 v[38:39], v[36:37]
	v_mov_b64_e32 v[36:37], v[34:35]
	v_mov_b64_e32 v[34:35], v[32:33]
	v_mfma_f32_32x32x16_bf16 v[82:97], v[212:215], v[104:107], v[82:97]
	s_waitcnt vmcnt(0)
	v_lshrrev_b32_e32 v132, v150, v132
	v_lshrrev_b32_e32 v133, v150, v133
	v_lshrrev_b32_e32 v134, v150, v134
	v_lshrrev_b32_e32 v135, v150, v135
	v_mfma_f32_32x32x16_bf16 v[34:49], v[204:207], v[100:103], v[34:49]
	v_mfma_f32_32x32x16_bf16 v[66:81], v[200:203], v[104:107], v[66:81]
	v_mfma_f32_32x32x16_bf16 v[50:65], v[190:193], v[104:107], v[50:65]
	v_mfma_f32_32x32x16_bf16 v[34:49], v[186:189], v[104:107], v[34:49]
	ds_read_b128 v[186:189], v185 offset:13920
	ds_read_b128 v[190:193], v185 offset:9312
	ds_read_b128 v[200:203], v185 offset:4704
	ds_read_b128 v[204:207], v185 offset:13888
	ds_read_b128 v[208:211], v185 offset:9280
	ds_read_b128 v[212:215], v185 offset:4672
	ds_read_b128 v[216:219], v185 offset:64
	ds_read_b128 v[220:223], v185 offset:96
	s_waitcnt lgkmcnt(0)
	s_nop 0
	v_mfma_f32_32x32x16_bf16 v[82:97], v[216:219], v[108:111], v[82:97]
	v_mfma_f32_32x32x16_bf16 v[82:97], v[220:223], v[112:115], v[82:97]
	v_mfma_f32_32x32x16_bf16 v[66:81], v[212:215], v[108:111], v[66:81]
	s_nop 10
	v_bfe_i32 v224, v132, 0, 1
	v_bfi_b32 v82, v224, v82, v235
	v_bfe_i32 v224, v132, 1, 1
	v_bfi_b32 v83, v224, v83, v235
	v_mfma_f32_32x32x16_bf16 v[66:81], v[200:203], v[112:115], v[66:81]
	v_bfe_i32 v224, v132, 2, 1
	v_bfi_b32 v84, v224, v84, v235
	v_bfe_i32 v224, v132, 3, 1
	v_bfi_b32 v85, v224, v85, v235
	v_mfma_f32_32x32x16_bf16 v[50:65], v[208:211], v[108:111], v[50:65]
	v_bfe_i32 v224, v132, 8, 1
	v_bfi_b32 v86, v224, v86, v235
	v_bfe_i32 v224, v132, 9, 1
	v_bfi_b32 v87, v224, v87, v235
	v_mfma_f32_32x32x16_bf16 v[50:65], v[190:193], v[112:115], v[50:65]
	v_bfe_i32 v224, v132, 10, 1
	v_bfi_b32 v88, v224, v88, v235
	v_bfe_i32 v224, v132, 11, 1
	v_bfi_b32 v89, v224, v89, v235
	v_mfma_f32_32x32x16_bf16 v[34:49], v[204:207], v[108:111], v[34:49]
	v_bfe_i32 v224, v132, 16, 1
	v_bfi_b32 v90, v224, v90, v235
	v_bfe_i32 v224, v132, 17, 1
	v_bfi_b32 v91, v224, v91, v235
	v_mfma_f32_32x32x16_bf16 v[34:49], v[186:189], v[112:115], v[34:49]
	v_bfe_i32 v224, v132, 18, 1
	v_bfi_b32 v92, v224, v92, v235
	v_bfe_i32 v224, v132, 19, 1
	v_bfi_b32 v93, v224, v93, v235
	v_bfe_i32 v224, v132, 24, 1
	v_bfi_b32 v94, v224, v94, v235
	v_bfe_i32 v224, v132, 25, 1
	v_bfi_b32 v95, v224, v95, v235
	v_bfe_i32 v224, v132, 26, 1
	v_bfi_b32 v96, v224, v96, v235
	v_bfe_i32 v224, v132, 27, 1
	v_bfi_b32 v97, v224, v97, v235
	v_bfe_i32 v224, v133, 0, 1
	v_bfi_b32 v66, v224, v66, v235
	v_bfe_i32 v224, v133, 1, 1
	v_bfi_b32 v67, v224, v67, v235
	v_bfe_i32 v224, v133, 2, 1
	v_bfi_b32 v68, v224, v68, v235
	v_bfe_i32 v224, v133, 3, 1
	v_bfi_b32 v69, v224, v69, v235
	v_bfe_i32 v224, v133, 8, 1
	v_bfi_b32 v70, v224, v70, v235
	v_bfe_i32 v224, v133, 9, 1
	v_bfi_b32 v71, v224, v71, v235
	v_bfe_i32 v224, v133, 10, 1
	v_bfi_b32 v72, v224, v72, v235
	v_bfe_i32 v224, v133, 11, 1
	v_bfi_b32 v73, v224, v73, v235
	v_bfe_i32 v224, v133, 16, 1
	v_bfi_b32 v74, v224, v74, v235
	v_bfe_i32 v224, v133, 17, 1
	v_bfi_b32 v75, v224, v75, v235
	v_bfe_i32 v224, v133, 18, 1
	v_bfi_b32 v76, v224, v76, v235
	v_bfe_i32 v224, v133, 19, 1
	v_bfi_b32 v77, v224, v77, v235
	v_bfe_i32 v224, v133, 24, 1
	v_bfi_b32 v78, v224, v78, v235
	v_bfe_i32 v224, v133, 25, 1
	v_bfi_b32 v79, v224, v79, v235
	v_bfe_i32 v224, v133, 26, 1
	v_bfi_b32 v80, v224, v80, v235
	v_bfe_i32 v224, v133, 27, 1
	v_bfi_b32 v81, v224, v81, v235
	v_bfe_i32 v224, v134, 0, 1
	v_bfi_b32 v50, v224, v50, v235
	v_bfe_i32 v224, v134, 1, 1
	v_bfi_b32 v51, v224, v51, v235
	v_bfe_i32 v224, v134, 2, 1
	v_bfi_b32 v52, v224, v52, v235
	v_bfe_i32 v224, v134, 3, 1
	v_bfi_b32 v53, v224, v53, v235
	v_bfe_i32 v224, v134, 8, 1
	v_bfi_b32 v54, v224, v54, v235
	v_bfe_i32 v224, v134, 9, 1
	v_bfi_b32 v55, v224, v55, v235
	v_bfe_i32 v224, v134, 10, 1
	v_bfi_b32 v56, v224, v56, v235
	v_bfe_i32 v224, v134, 11, 1
	v_bfi_b32 v57, v224, v57, v235
	v_bfe_i32 v224, v134, 16, 1
	v_bfi_b32 v58, v224, v58, v235
	v_bfe_i32 v224, v134, 17, 1
	v_bfi_b32 v59, v224, v59, v235
	v_bfe_i32 v224, v134, 18, 1
	v_bfi_b32 v60, v224, v60, v235
	v_bfe_i32 v224, v134, 19, 1
	v_bfi_b32 v61, v224, v61, v235
	v_bfe_i32 v224, v134, 24, 1
; DI float shx(float v, int o, int lane) { return __int_as_float(__builtin_amdgcn_ds_bpermute((lane ^ o) << 2, __float_as_int(v))); }
; DI int crow(int i, int h) { return (i & 3) + 8 * (i >> 2) + 4 * h; }
;     ...
;                 for (int kb2 = 0; kb2 < NKB; ++kb2) {
;                     const unsigned wsel = ((kb2 & 1) ? (unsigned)(mw[kb2 >> 1] >> 32) : (unsigned)mw[kb2 >> 1]) >> (4 * h);
; #pragma unroll
;                     for (int i = 0; i < 16; ++i) { const int cb = (i & 3) + 8 * (i >> 2); if (!((wsel >> cb) & 1u)) sv[kb2][i] = -1e30f; }
;                 }
;             } else if (key0 + 32 * NKB - 1 > q0) {
;                 const int qq = q0 + r;
; #pragma unroll
;                 for (int kb2 = 0; kb2 < NKB; ++kb2)
; #pragma unroll
;                     for (int i = 0; i < 16; ++i) { if (key0 + 32 * kb2 + crow(i, h) > qq) sv[kb2][i] = -1e30f; }
;             }
;             float mx = -1e30f;
; #pragma unroll
;             for (int kb2 = 0; kb2 < NKB; ++kb2)
; #pragma unroll
;                 for (int i = 0; i < 16; ++i) mx = __builtin_fmaxf(mx, sv[kb2][i]);
;             mx = __builtin_fmaxf(mx, shx(mx, 32, lane));
;             if (__ballot(mx > 8.0f)) {
;                 const float delta = __builtin_fmaxf(mx, 0.f);
;                 const float alpha = __builtin_amdgcn_exp2f(-delta);
;                 nm_run -= delta; l_run *= alpha;
; #pragma unroll
;                 for (int kb2 = 0; kb2 < NKB; ++kb2)
; #pragma unroll
;                     for (int i = 0; i < 16; ++i) sv[kb2][i] -= delta;
; #pragma unroll
;                 for (int db = 0; db < NDB; ++db)
; #pragma unroll
;                     for (int i = 0; i < 16; ++i) ot[db][i] *= alpha;
;             }
	v_bfi_b32 v62, v224, v62, v235
	v_bfe_i32 v224, v134, 25, 1
	v_bfi_b32 v63, v224, v63, v235
	v_bfe_i32 v224, v134, 26, 1
	v_bfi_b32 v64, v224, v64, v235
	v_bfe_i32 v224, v134, 27, 1
	v_bfi_b32 v65, v224, v65, v235
	v_bfe_i32 v224, v135, 0, 1
	v_bfi_b32 v34, v224, v34, v235
	v_bfe_i32 v224, v135, 1, 1
	v_bfi_b32 v35, v224, v35, v235
	v_bfe_i32 v224, v135, 2, 1
	v_bfi_b32 v36, v224, v36, v235
	v_bfe_i32 v224, v135, 3, 1
	v_bfi_b32 v37, v224, v37, v235
	v_bfe_i32 v224, v135, 8, 1
	v_bfi_b32 v38, v224, v38, v235
	v_bfe_i32 v224, v135, 9, 1
	v_bfi_b32 v39, v224, v39, v235
	v_bfe_i32 v224, v135, 10, 1
	v_bfi_b32 v40, v224, v40, v235
	v_bfe_i32 v224, v135, 11, 1
	v_bfi_b32 v41, v224, v41, v235
	v_bfe_i32 v224, v135, 16, 1
	v_bfi_b32 v42, v224, v42, v235
	v_bfe_i32 v224, v135, 17, 1
	v_bfi_b32 v43, v224, v43, v235
	v_bfe_i32 v224, v135, 18, 1
	v_bfi_b32 v44, v224, v44, v235
	v_bfe_i32 v224, v135, 19, 1
	v_bfi_b32 v45, v224, v45, v235
	v_bfe_i32 v224, v135, 24, 1
	v_bfi_b32 v46, v224, v46, v235
	v_bfe_i32 v224, v135, 25, 1
	v_bfi_b32 v47, v224, v47, v235
	v_bfe_i32 v224, v135, 26, 1
	v_bfi_b32 v48, v224, v48, v235
	v_max3_f32 v33, v82, s61, v83
	v_max3_f32 v33, v33, v84, v85
	v_max3_f32 v33, v33, v86, v87
	v_max3_f32 v33, v33, v88, v89
	v_max3_f32 v33, v33, v90, v91
	v_max3_f32 v33, v33, v92, v93
	v_max3_f32 v33, v33, v94, v95
	v_max3_f32 v33, v33, v96, v97
	v_max3_f32 v33, v33, v66, v67
	v_max3_f32 v33, v33, v68, v69
	v_max3_f32 v33, v33, v70, v71
	v_max3_f32 v33, v33, v72, v73
	v_max3_f32 v33, v33, v74, v75
	v_max3_f32 v33, v33, v76, v77
	v_max3_f32 v33, v33, v78, v79
	v_max3_f32 v33, v33, v80, v81
	v_max3_f32 v33, v33, v50, v51
	v_max3_f32 v33, v33, v52, v53
	v_max3_f32 v33, v33, v54, v55
	v_max3_f32 v33, v33, v56, v57
	v_max3_f32 v33, v33, v58, v59
	v_max3_f32 v33, v33, v60, v61
	v_max3_f32 v33, v33, v62, v63
	v_max3_f32 v33, v33, v64, v65
	v_max3_f32 v33, v33, v34, v35
	v_max3_f32 v33, v33, v36, v37
	v_max3_f32 v33, v33, v38, v39
	v_max3_f32 v33, v33, v40, v41
	v_max3_f32 v33, v33, v42, v43
	v_max3_f32 v33, v33, v44, v45
	v_bfe_i32 v224, v135, 27, 1
	v_bfi_b32 v49, v224, v49, v235
	v_max3_f32 v33, v33, v46, v47
	v_max3_f32 v33, v33, v48, v49
	v_mov_b32_e32 v132, v33
	v_mov_b32_e32 v224, v33
	s_nop 1
	v_permlane32_swap_b32 v132, v224
	s_nop 1
	v_max_f32_e32 v33, v132, v224
	s_waitcnt lgkmcnt(0)
	v_cmp_lt_f32_e32 vcc, s33, v33
	s_cbranch_vccz .LBB0_524
	v_max_f32_e32 v33, v33, v33
	v_max_f32_e32 v132, 0, v33
	v_exp_f32_e64 v134, -v132
	v_sub_f32_e32 v32, v32, v132
	v_pk_add_f32 v[82:83], v[82:83], v[132:133] op_sel_hi:[1,0] neg_lo:[0,1] neg_hi:[0,1]
	v_pk_add_f32 v[84:85], v[84:85], v[132:133] op_sel_hi:[1,0] neg_lo:[0,1] neg_hi:[0,1]
	v_pk_add_f32 v[86:87], v[86:87], v[132:133] op_sel_hi:[1,0] neg_lo:[0,1] neg_hi:[0,1]
	v_pk_add_f32 v[88:89], v[88:89], v[132:133] op_sel_hi:[1,0] neg_lo:[0,1] neg_hi:[0,1]
	v_pk_add_f32 v[90:91], v[90:91], v[132:133] op_sel_hi:[1,0] neg_lo:[0,1] neg_hi:[0,1]
	v_pk_add_f32 v[92:93], v[92:93], v[132:133] op_sel_hi:[1,0] neg_lo:[0,1] neg_hi:[0,1]
	v_pk_add_f32 v[94:95], v[94:95], v[132:133] op_sel_hi:[1,0] neg_lo:[0,1] neg_hi:[0,1]
	v_pk_add_f32 v[96:97], v[96:97], v[132:133] op_sel_hi:[1,0] neg_lo:[0,1] neg_hi:[0,1]
	v_pk_add_f32 v[66:67], v[66:67], v[132:133] op_sel_hi:[1,0] neg_lo:[0,1] neg_hi:[0,1]
	v_pk_add_f32 v[68:69], v[68:69], v[132:133] op_sel_hi:[1,0] neg_lo:[0,1] neg_hi:[0,1]
	v_pk_add_f32 v[70:71], v[70:71], v[132:133] op_sel_hi:[1,0] neg_lo:[0,1] neg_hi:[0,1]
	v_pk_add_f32 v[72:73], v[72:73], v[132:133] op_sel_hi:[1,0] neg_lo:[0,1] neg_hi:[0,1]
	v_pk_add_f32 v[74:75], v[74:75], v[132:133] op_sel_hi:[1,0] neg_lo:[0,1] neg_hi:[0,1]
	v_pk_add_f32 v[76:77], v[76:77], v[132:133] op_sel_hi:[1,0] neg_lo:[0,1] neg_hi:[0,1]
	v_pk_add_f32 v[78:79], v[78:79], v[132:133] op_sel_hi:[1,0] neg_lo:[0,1] neg_hi:[0,1]
	v_pk_add_f32 v[80:81], v[80:81], v[132:133] op_sel_hi:[1,0] neg_lo:[0,1] neg_hi:[0,1]
	v_pk_add_f32 v[50:51], v[50:51], v[132:133] op_sel_hi:[1,0] neg_lo:[0,1] neg_hi:[0,1]
	v_pk_add_f32 v[52:53], v[52:53], v[132:133] op_sel_hi:[1,0] neg_lo:[0,1] neg_hi:[0,1]
	v_pk_add_f32 v[54:55], v[54:55], v[132:133] op_sel_hi:[1,0] neg_lo:[0,1] neg_hi:[0,1]
	v_pk_add_f32 v[56:57], v[56:57], v[132:133] op_sel_hi:[1,0] neg_lo:[0,1] neg_hi:[0,1]
	v_pk_add_f32 v[58:59], v[58:59], v[132:133] op_sel_hi:[1,0] neg_lo:[0,1] neg_hi:[0,1]
	v_pk_add_f32 v[60:61], v[60:61], v[132:133] op_sel_hi:[1,0] neg_lo:[0,1] neg_hi:[0,1]
	v_pk_add_f32 v[62:63], v[62:63], v[132:133] op_sel_hi:[1,0] neg_lo:[0,1] neg_hi:[0,1]
	v_pk_add_f32 v[64:65], v[64:65], v[132:133] op_sel_hi:[1,0] neg_lo:[0,1] neg_hi:[0,1]
	v_pk_add_f32 v[34:35], v[34:35], v[132:133] op_sel_hi:[1,0] neg_lo:[0,1] neg_hi:[0,1]
	v_pk_add_f32 v[36:37], v[36:37], v[132:133] op_sel_hi:[1,0] neg_lo:[0,1] neg_hi:[0,1]
	v_pk_add_f32 v[38:39], v[38:39], v[132:133] op_sel_hi:[1,0] neg_lo:[0,1] neg_hi:[0,1]
	v_pk_add_f32 v[40:41], v[40:41], v[132:133] op_sel_hi:[1,0] neg_lo:[0,1] neg_hi:[0,1]
	v_pk_add_f32 v[42:43], v[42:43], v[132:133] op_sel_hi:[1,0] neg_lo:[0,1] neg_hi:[0,1]
	v_pk_add_f32 v[44:45], v[44:45], v[132:133] op_sel_hi:[1,0] neg_lo:[0,1] neg_hi:[0,1]
	v_pk_add_f32 v[46:47], v[46:47], v[132:133] op_sel_hi:[1,0] neg_lo:[0,1] neg_hi:[0,1]
	v_pk_add_f32 v[48:49], v[48:49], v[132:133] op_sel_hi:[1,0] neg_lo:[0,1] neg_hi:[0,1]
	v_pk_mul_f32 v[14:15], v[14:15], v[134:135] op_sel_hi:[1,0]
	v_pk_mul_f32 v[12:13], v[12:13], v[134:135] op_sel_hi:[1,0]
	v_pk_mul_f32 v[10:11], v[10:11], v[134:135] op_sel_hi:[1,0]
	v_pk_mul_f32 v[8:9], v[8:9], v[134:135] op_sel_hi:[1,0]
	v_pk_mul_f32 v[6:7], v[6:7], v[134:135] op_sel_hi:[1,0]
	v_pk_mul_f32 v[4:5], v[4:5], v[134:135] op_sel_hi:[1,0]
	v_pk_mul_f32 v[2:3], v[2:3], v[134:135] op_sel_hi:[1,0]
	v_pk_mul_f32 v[0:1], v[0:1], v[134:135] op_sel_hi:[1,0]
	v_pk_mul_f32 v[30:31], v[30:31], v[134:135] op_sel_hi:[1,0]
	v_pk_mul_f32 v[28:29], v[28:29], v[134:135] op_sel_hi:[1,0]
	v_pk_mul_f32 v[26:27], v[26:27], v[134:135] op_sel_hi:[1,0]
	v_pk_mul_f32 v[24:25], v[24:25], v[134:135] op_sel_hi:[1,0]
	v_pk_mul_f32 v[22:23], v[22:23], v[134:135] op_sel_hi:[1,0]
	v_pk_mul_f32 v[20:21], v[20:21], v[134:135] op_sel_hi:[1,0]
	v_pk_mul_f32 v[18:19], v[18:19], v[134:135] op_sel_hi:[1,0]
	v_pk_mul_f32 v[16:17], v[16:17], v[134:135] op_sel_hi:[1,0]
	v_mul_f32_e32 v184, v184, v134
